# context-row fix-up after the out-projection: all 23 loads of an item issued up front (was 11 serial round trips), sums in the original order
# baseline (speedup 1.0000x reference)
; __device__ __forceinline__ unsigned pk2(float lo, float hi) { return pg8::pkbf(lo, hi); }
; __device__ __forceinline__ void phase_ctxfix(bf16* X, bf16* HX, unsigned long long* rowss, const float* slab, const float* fixgate, const float* g, const float* nsc, int gw, int NGW, int lane) {
;     ...
;         const int cr = it >> 2, col = 512 * (it & 3) + 8 * lane;
;         const int b = cr / CTX, p = cr - b * CTX; const size_t r = (size_t)b * TB + p;
;         const float* sp = slab + (size_t)cr * DM + col;
;         f32x4 a0 = *(const f32x4*)sp, a1 = *(const f32x4*)(sp + 4);
; #pragma unroll
;         for (int s2 = 1; s2 < 8; ++s2) { a0 = a0 + *(const f32x4*)(sp + (size_t)s2 * 1024 * DM); a1 = a1 + *(const f32x4*)(sp + (size_t)s2 * 1024 * DM + 4); }
;         const v4u xw = *(const v4u*)(X + r * DM + col);
;         const f32x4 x0 = {__uint_as_float(xw.x << 16), __uint_as_float(xw.x & 0xffff0000u), __uint_as_float(xw.y << 16), __uint_as_float(xw.y & 0xffff0000u)};
;         const f32x4 x1 = {__uint_as_float(xw.z << 16), __uint_as_float(xw.z & 0xffff0000u), __uint_as_float(xw.w << 16), __uint_as_float(xw.w & 0xffff0000u)};
;         const f32x4 v0 = x0 + *(const f32x4*)(fixgate + col) * a0, v1 = x1 + *(const f32x4*)(fixgate + col + 4) * a1;
;         float ss = ((v0.x * v0.x + v0.y * v0.y) + (v0.z * v0.z + v0.w * v0.w)) + ((v1.x * v1.x + v1.y * v1.y) + (v1.z * v1.z + v1.w * v1.w));
;         ss = wave_sum(ss); if (lane == 0) atomicAdd(rowss + r, (unsigned long long)(ss * 16777216.f));
;         *(v4u*)(X + r * DM + col) = (v4u){pk2(v0.x, v0.y), pk2(v0.z, v0.w), pk2(v1.x, v1.y), pk2(v1.z, v1.w)};
;         const f32x4 h0 = v0 * (*(const f32x4*)(g + col) * (*(const f32x4*)(nsc + col) + 1.f)), h1 = v1 * (*(const f32x4*)(g + col + 4) * (*(const f32x4*)(nsc + col + 4) + 1.f));
;         *(v4u*)(HX + r * DM + col) = (v4u){pk2(h0.x, h0.y), pk2(h0.z, h0.w), pk2(h1.x, h1.y), pk2(h1.z, h1.w)};
.LBB0_1247:
	s_or_b64 exec, exec, s[16:17]
	s_waitcnt lgkmcnt(0)
	v_mov_b32_e32 v3, v33
	v_lshl_add_u64 v[12:13], s[14:15], 0, v[2:3]
	v_cvt_pk_bf16_f32 v22, v6, v7
	v_cvt_pk_bf16_f32 v23, v4, v5
	v_cvt_pk_bf16_f32 v24, v10, v11
	v_cvt_pk_bf16_f32 v25, v8, v9
	global_store_dwordx4 v[12:13], v[22:25], off
	s_nop 0
	s_lshl_b64 s[4:5], s[12:13], 11
	s_lshl_b64 s[4:5], s[4:5], 1
	s_add_u32 s4, s80, s4
	s_addc_u32 s5, s81, s5
	s_add_i32 s2, s2, s76
	s_cmpk_lt_i32 s2, 0x1000
	v_pk_add_f32 v[12:13], v[124:125], 1.0 op_sel_hi:[1,0]
	v_pk_add_f32 v[22:23], v[122:123], 1.0 op_sel_hi:[1,0]
	v_pk_add_f32 v[24:25], v[128:129], 1.0 op_sel_hi:[1,0]
	v_pk_add_f32 v[26:27], v[126:127], 1.0 op_sel_hi:[1,0]
	v_pk_mul_f32 v[12:13], v[132:133], v[12:13]
	v_pk_mul_f32 v[22:23], v[130:131], v[22:23]
	v_pk_mul_f32 v[24:25], v[136:137], v[24:25]
	v_pk_mul_f32 v[26:27], v[134:135], v[26:27]
	v_pk_mul_f32 v[12:13], v[4:5], v[12:13]
	v_pk_mul_f32 v[4:5], v[6:7], v[22:23]
	v_pk_mul_f32 v[8:9], v[8:9], v[24:25]
	v_pk_mul_f32 v[6:7], v[10:11], v[26:27]
	v_cvt_pk_bf16_f32 v4, v4, v5
	v_cvt_pk_bf16_f32 v5, v12, v13
	v_cvt_pk_bf16_f32 v6, v6, v7
	v_cvt_pk_bf16_f32 v7, v8, v9
	global_store_dwordx4 v2, v[4:7], s[4:5]
	s_cbranch_scc0 .LBB0_1253
.LBB0_1248:
	s_lshl_b32 s3, s2, 9
	s_and_b32 s3, s3, 0x600
	v_or_b32_e32 v1, s3, v14
	s_ashr_i32 s3, s2, 31
	s_ashr_i32 s4, s2, 2
	s_lshr_b32 s3, s3, 24
	s_add_i32 s5, s4, s3
	s_ashr_i32 s3, s5, 8
	s_and_b32 s5, s5, 0xffffff00
	s_sub_i32 s12, s4, s5
	s_ashr_i32 s5, s4, 31
	s_ashr_i32 s13, s12, 31
	s_lshl_b64 s[4:5], s[4:5], 13
	s_add_u32 s4, s33, s4
	s_addc_u32 s5, s42, s5
	v_lshlrev_b32_e32 v32, 2, v1
	v_lshl_add_u64 v[26:27], s[4:5], 0, v[32:33]
	global_load_dwordx4 v[142:145], v32, s[4:5] offset:16
	global_load_dwordx4 v[138:141], v32, s[4:5]
	s_mov_b64 s[4:5], 0x800000
	v_lshl_add_u64 v[10:11], v[26:27], 0, s[4:5]
	s_mov_b64 s[4:5], 0x1000000
	v_lshl_add_u64 v[12:13], v[26:27], 0, s[4:5]
	s_mov_b64 s[4:5], 0x1800000
	v_lshl_add_u64 v[22:23], v[26:27], 0, s[4:5]
	s_mov_b64 s[4:5], 0x2000000
	v_lshl_add_u64 v[24:25], v[26:27], 0, s[4:5]
	s_mov_b64 s[4:5], 0x2800000
	v_lshl_add_u64 v[28:29], v[26:27], 0, s[4:5]
	s_mov_b64 s[4:5], 0x3000000
	v_lshl_add_u64 v[30:31], v[26:27], 0, s[4:5]
	s_mov_b64 s[4:5], 0x3800000
	v_lshl_add_u64 v[34:35], v[26:27], 0, s[4:5]
	global_load_dwordx4 v[38:41], v[10:11], off
	global_load_dwordx4 v[42:45], v[10:11], off offset:16
	global_load_dwordx4 v[46:49], v[12:13], off
	global_load_dwordx4 v[50:53], v[12:13], off offset:16
	global_load_dwordx4 v[54:57], v[22:23], off
	global_load_dwordx4 v[58:61], v[22:23], off offset:16
	global_load_dwordx4 v[62:65], v[24:25], off
	global_load_dwordx4 v[66:69], v[24:25], off offset:16
	global_load_dwordx4 v[70:73], v[28:29], off
	global_load_dwordx4 v[74:77], v[28:29], off offset:16
	global_load_dwordx4 v[78:81], v[30:31], off
	global_load_dwordx4 v[82:85], v[30:31], off offset:16
	global_load_dwordx4 v[86:89], v[34:35], off
	global_load_dwordx4 v[90:93], v[34:35], off offset:16
	s_mul_hi_i32 s4, s3, 0x2100
	s_mulk_i32 s3, 0x2100
	s_add_u32 s12, s3, s12
	s_addc_u32 s13, s4, s13
	s_lshl_b64 s[4:5], s[12:13], 12
	s_add_u32 s14, s72, s4
	s_addc_u32 s15, s73, s5
	v_lshlrev_b32_e32 v2, 1, v1
	global_load_dwordx4 v[110:113], v2, s[14:15]
	global_load_dwordx4 v[114:117], v32, s[6:7]
	global_load_dwordx4 v[118:121], v32, s[6:7] offset:16
	global_load_dwordx4 v[122:125], v32, s[8:9]
	global_load_dwordx4 v[126:129], v32, s[8:9] offset:16
	global_load_dwordx4 v[130:133], v32, s[10:11]
	global_load_dwordx4 v[134:137], v32, s[10:11] offset:16
	s_waitcnt vmcnt(19)
	v_pk_add_f32 v[10:11], v[138:139], v[38:39]
	v_pk_add_f32 v[22:23], v[142:143], v[42:43]
	v_pk_add_f32 v[12:13], v[140:141], v[40:41]
	v_pk_add_f32 v[24:25], v[144:145], v[44:45]
	s_waitcnt vmcnt(17)
	v_pk_add_f32 v[10:11], v[10:11], v[46:47]
	v_pk_add_f32 v[22:23], v[22:23], v[50:51]
	v_pk_add_f32 v[12:13], v[12:13], v[48:49]
	v_pk_add_f32 v[24:25], v[24:25], v[52:53]
	s_waitcnt vmcnt(15)
	v_pk_add_f32 v[10:11], v[10:11], v[54:55]
	v_pk_add_f32 v[22:23], v[22:23], v[58:59]
	v_pk_add_f32 v[12:13], v[12:13], v[56:57]
	v_pk_add_f32 v[24:25], v[24:25], v[60:61]
	s_waitcnt vmcnt(13)
	v_pk_add_f32 v[10:11], v[10:11], v[62:63]
	v_pk_add_f32 v[22:23], v[22:23], v[66:67]
	v_pk_add_f32 v[12:13], v[12:13], v[64:65]
	v_pk_add_f32 v[24:25], v[24:25], v[68:69]
	s_waitcnt vmcnt(11)
	v_pk_add_f32 v[10:11], v[10:11], v[70:71]
	v_pk_add_f32 v[22:23], v[22:23], v[74:75]
	v_pk_add_f32 v[12:13], v[12:13], v[72:73]
	v_pk_add_f32 v[24:25], v[24:25], v[76:77]
	s_waitcnt vmcnt(9)
	v_pk_add_f32 v[10:11], v[10:11], v[78:79]
	v_pk_add_f32 v[22:23], v[22:23], v[82:83]
	v_pk_add_f32 v[12:13], v[12:13], v[80:81]
	v_pk_add_f32 v[24:25], v[24:25], v[84:85]
	s_waitcnt vmcnt(0)
	v_pk_add_f32 v[28:29], v[10:11], v[86:87]
	v_pk_add_f32 v[26:27], v[12:13], v[88:89]
	v_pk_add_f32 v[22:23], v[22:23], v[90:91]
	v_pk_add_f32 v[24:25], v[24:25], v[92:93]
	v_lshlrev_b32_e32 v34, 16, v112
	v_and_b32_e32 v35, 0xffff0000, v112
	v_lshlrev_b32_e32 v36, 16, v113
	v_and_b32_e32 v37, 0xffff0000, v113
	v_lshlrev_b32_e32 v30, 16, v110
	v_and_b32_e32 v31, 0xffff0000, v110
	v_lshlrev_b32_e32 v4, 16, v111
	v_and_b32_e32 v5, 0xffff0000, v111
	v_pk_fma_f32 v[10:11], v[22:23], v[118:119], v[34:35]
	v_pk_fma_f32 v[4:5], v[26:27], v[116:117], v[4:5]
	v_pk_fma_f32 v[6:7], v[28:29], v[114:115], v[30:31]
	v_mul_f32_e32 v3, v5, v5
	v_mul_f32_e32 v1, v7, v7
	v_pk_fma_f32 v[8:9], v[24:25], v[120:121], v[36:37]
	v_fmac_f32_e32 v1, v6, v6
	v_fmac_f32_e32 v3, v4, v4
	v_add_f32_e32 v1, v1, v3
	v_mul_f32_e32 v3, v11, v11
	v_mul_f32_e32 v12, v9, v9
	v_fmac_f32_e32 v3, v10, v10
	v_fmac_f32_e32 v12, v8, v8
	v_add_f32_e32 v3, v3, v12
	v_add_f32_e32 v1, v1, v3
	ds_bpermute_b32 v3, v15, v1
	s_waitcnt lgkmcnt(0)
	v_add_f32_e32 v1, v1, v3
	ds_bpermute_b32 v3, v16, v1
	s_waitcnt lgkmcnt(0)
	v_add_f32_e32 v1, v1, v3
	ds_bpermute_b32 v3, v17, v1
	s_waitcnt lgkmcnt(0)
	v_add_f32_e32 v1, v1, v3
	ds_bpermute_b32 v3, v18, v1
	s_waitcnt lgkmcnt(0)
	v_add_f32_e32 v1, v1, v3
	ds_bpermute_b32 v3, v19, v1
	s_waitcnt lgkmcnt(0)
	v_add_f32_e32 v1, v1, v3
	ds_bpermute_b32 v3, v20, v1
	s_and_saveexec_b64 s[16:17], vcc
	s_cbranch_execz .LBB0_1247
	s_waitcnt lgkmcnt(0)
	v_add_f32_e32 v1, v1, v3
	v_mul_f32_e32 v1, 0x4b800000, v1
	v_trunc_f32_e32 v1, v1
	v_mul_f32_e32 v3, 0x2f800000, v1
	v_floor_f32_e32 v3, v3
	v_fmac_f32_e32 v1, 0xcf800000, v3
	v_cvt_u32_f32_e32 v12, v1
	v_cvt_u32_f32_e32 v1, v3
	s_mov_b64 s[4:5], exec
	s_mov_b64 s[18:19], 0
